# conformer conv: bias load issued at the unit start with the tile loads instead of one exposed round trip before the tap loop
# baseline (speedup 1.0000x reference)
; #define LAS __attribute__((address_space(3)))
; #define SG(x) __builtin_amdgcn_rcpf(1.f + __builtin_amdgcn_exp2f((x) * -1.4426950408889634f))
; __device__ void conv_unit(LAS unsigned char* lds, const bf16_t* __restrict__ Z, bf16_t* __restrict__ MIX, int unit,
;                           const float* __restrict__ ccw, const float* __restrict__ ccb, const float* __restrict__ lng, const float* __restrict__ lnb, const float* __restrict__ scw) {
;     ...
;     { u32x4 cav[6], cgv[6];
; #pragma unroll
;       for (int i = 0; i < 6; ++i) { const int id = tid + 512 * i, row = id >> 5, c8 = (id & 31) * 8; int gr = t0 - 30 + row; gr = gr < 0 ? 0 : gr; gr = gr > MTOK - 1 ? MTOK - 1 : gr;
;           const bf16_t* zr = Z + (size_t)gr * DIN + 1536 + c8; cav[i] = *(const u32x4*)zr; cgv[i] = *(const u32x4*)(zr + 256); }
; #pragma unroll
;       for (int i = 0; i < 6; ++i) { const int id = tid + 512 * i, row = id >> 5, c8 = (id & 31) * 8, tp = tpos0 - 30 + row; const u32x4 ca = cav[i], cg = cgv[i];
;           f32x4 a, b;
;           a[0] = bflo(ca.x) * SG(bflo(cg.x)); a[1] = bfhi(ca.x) * SG(bfhi(cg.x)); a[2] = bflo(ca.y) * SG(bflo(cg.y)); a[3] = bfhi(ca.y) * SG(bfhi(cg.y));
;           b[0] = bflo(ca.z) * SG(bflo(cg.z)); b[1] = bfhi(ca.z) * SG(bfhi(cg.z)); b[2] = bflo(ca.w) * SG(bflo(cg.w)); b[3] = bfhi(ca.w) * SG(bfhi(cg.w));
;           if (tp < 0) { a = (f32x4){0.f, 0.f, 0.f, 0.f}; b = a; }
;           if (id < 94 * 32) { *(LAS f32x4*)(ub + row * 256 + c8) = a; *(LAS f32x4*)(ub + row * 256 + c8 + 4) = b; } } }
;     ...
;     __syncthreads();
;     { const int ch = tid & 255, half = tid >> 8; float acc[32]; const float bias = ccb[ch];
.Lcv_tap_done:
	v_lshlrev_b32_e32 v69, 2, v187
	v_and_b32_e32 v69, 0x3fc, v69
	global_load_dword v68, v69, s[0:1]
	v_lshl_add_u64 v[2:3], v[0:1], 1, s[10:11]
	v_lshlrev_b32_e32 v0, 1, v101
	v_lshl_add_u64 v[2:3], v[2:3], 0, v[0:1]
	global_load_dwordx4 v[34:37], v[2:3], off offset:3072
	global_load_dwordx4 v[38:41], v[2:3], off offset:3584
	v_add_u32_e32 v2, 0x400, v100
	v_ashrrev_i32_e32 v50, 5, v2
	v_add_u32_e32 v2, s14, v50
	v_med3_i32 v2, v2, 0, v194
	v_mul_u32_u24_e32 v2, 0xb00, v2
	v_mov_b32_e32 v3, v1
	v_lshl_add_u64 v[2:3], v[2:3], 1, s[10:11]
	v_lshl_add_u64 v[2:3], v[2:3], 0, v[0:1]
	global_load_dwordx4 v[26:29], v[2:3], off offset:3072
	global_load_dwordx4 v[30:33], v[2:3], off offset:3584
	v_add_u32_e32 v2, 0x600, v100
	v_ashrrev_i32_e32 v49, 5, v2
	v_add_u32_e32 v2, s14, v49
	v_med3_i32 v2, v2, 0, v194
	v_mul_u32_u24_e32 v2, 0xb00, v2
	v_mov_b32_e32 v3, v1
	v_lshl_add_u64 v[2:3], v[2:3], 1, s[10:11]
	v_lshl_add_u64 v[2:3], v[2:3], 0, v[0:1]
	global_load_dwordx4 v[18:21], v[2:3], off offset:3072
	global_load_dwordx4 v[22:25], v[2:3], off offset:3584
	v_add_u32_e32 v2, 0x800, v100
	v_ashrrev_i32_e32 v48, 5, v2
	v_add_u32_e32 v2, s14, v48
	v_med3_i32 v2, v2, 0, v194
	v_mul_u32_u24_e32 v2, 0xb00, v2
	v_mov_b32_e32 v3, v1
	v_lshl_add_u64 v[2:3], v[2:3], 1, s[10:11]
	v_lshl_add_u64 v[2:3], v[2:3], 0, v[0:1]
	global_load_dwordx4 v[10:13], v[2:3], off offset:3072
	global_load_dwordx4 v[14:17], v[2:3], off offset:3584
	v_add_u32_e32 v2, 0xa00, v100
	v_ashrrev_i32_e32 v46, 5, v2
	v_add_u32_e32 v2, s14, v46
	v_med3_i32 v2, v2, 0, v194
	v_mul_u32_u24_e32 v2, 0xb00, v2
	v_mov_b32_e32 v3, v1
	v_lshl_add_u64 v[2:3], v[2:3], 1, s[10:11]
	v_lshl_add_u64 v[6:7], v[2:3], 0, v[0:1]
	global_load_dwordx4 v[2:5], v[6:7], off offset:3072
	s_nop 0
	global_load_dwordx4 v[6:9], v[6:7], off offset:3584
	s_and_b32 s18, s17, 0xfc0
	s_movk_i32 s10, 0xbc0
	v_lshl_add_u32 v47, v101, 2, 0
	s_sub_i32 s3, 30, s18
	v_cmp_gt_i32_e32 vcc, s10, v100
	s_and_saveexec_b64 s[10:11], vcc
	s_cbranch_execz .LBB0_129
	v_ashrrev_i32_e32 v44, 5, v100
	v_add_u32_e32 v42, s14, v44
	v_max_i32_e32 v42, 0, v42
	s_movk_i32 s14, 0xb00
	v_mul_lo_u32 v42, v42, s14
	v_readlane_b32 s14, v252, 20
	v_mov_b32_e32 v43, v1
	v_readlane_b32 s15, v252, 21
	v_lshl_add_u32 v60, v44, 10, v47
	v_cmp_gt_i32_e32 vcc, s3, v44
	v_lshl_add_u64 v[42:43], v[42:43], 1, s[14:15]
	v_lshl_add_u64 v[42:43], v[42:43], 0, v[0:1]
	global_load_dwordx4 v[52:55], v[42:43], off offset:3584
	global_load_dwordx4 v[56:59], v[42:43], off offset:3072
	s_waitcnt vmcnt(1)
	v_lshlrev_b32_e32 v42, 16, v52
	v_and_b32_e32 v43, 0xffff0000, v52
	v_mul_f32_e32 v42, 0xbfb8aa3b, v42
	v_mul_f32_e32 v43, 0xbfb8aa3b, v43
	v_exp_f32_e32 v42, v42
	v_exp_f32_e32 v43, v43
	s_waitcnt vmcnt(0)
	v_lshlrev_b32_e32 v44, 16, v56
	v_and_b32_e32 v45, 0xffff0000, v56
	v_add_f32_e32 v42, 1.0, v42
	v_add_f32_e32 v43, 1.0, v43
	v_rcp_f32_e32 v42, v42
	v_rcp_f32_e32 v43, v43
	v_lshlrev_b32_e32 v52, 16, v57
	v_lshlrev_b32_e32 v56, 16, v58
	v_pk_mul_f32 v[42:43], v[42:43], v[44:45]
	v_lshlrev_b32_e32 v44, 16, v53
	v_and_b32_e32 v45, 0xffff0000, v53
	v_mul_f32_e32 v44, 0xbfb8aa3b, v44
	v_mul_f32_e32 v45, 0xbfb8aa3b, v45
	v_exp_f32_e32 v44, v44
	v_exp_f32_e32 v45, v45
	v_and_b32_e32 v53, 0xffff0000, v57
	v_and_b32_e32 v57, 0xffff0000, v58
	v_add_f32_e32 v44, 1.0, v44
	v_add_f32_e32 v45, 1.0, v45
	v_rcp_f32_e32 v44, v44
	v_rcp_f32_e32 v45, v45
	v_cndmask_b32_e64 v43, v43, 0, vcc
	v_cndmask_b32_e64 v42, v42, 0, vcc
	v_pk_mul_f32 v[44:45], v[44:45], v[52:53]
	v_lshlrev_b32_e32 v52, 16, v54
	v_and_b32_e32 v53, 0xffff0000, v54
	v_mul_f32_e32 v52, 0xbfb8aa3b, v52
	v_mul_f32_e32 v53, 0xbfb8aa3b, v53
	v_lshlrev_b32_e32 v54, 16, v55
	v_and_b32_e32 v55, 0xffff0000, v55
	v_exp_f32_e32 v52, v52
	v_exp_f32_e32 v53, v53
	v_mul_f32_e32 v54, 0xbfb8aa3b, v54
	v_mul_f32_e32 v55, 0xbfb8aa3b, v55
	v_exp_f32_e32 v54, v54
	v_exp_f32_e32 v55, v55
	v_add_f32_e32 v52, 1.0, v52
	v_add_f32_e32 v53, 1.0, v53
	v_rcp_f32_e32 v52, v52
	v_rcp_f32_e32 v53, v53
	v_add_f32_e32 v54, 1.0, v54
	v_add_f32_e32 v55, 1.0, v55
	v_rcp_f32_e32 v54, v54
	v_rcp_f32_e32 v55, v55
	v_pk_mul_f32 v[52:53], v[52:53], v[56:57]
	v_lshlrev_b32_e32 v56, 16, v59
	v_and_b32_e32 v57, 0xffff0000, v59
	v_cndmask_b32_e64 v45, v45, 0, vcc
	v_cndmask_b32_e64 v44, v44, 0, vcc
	v_pk_mul_f32 v[54:55], v[54:55], v[56:57]
	v_cndmask_b32_e64 v53, v53, 0, vcc
	v_cndmask_b32_e64 v55, v55, 0, vcc
	v_cndmask_b32_e64 v54, v54, 0, vcc
	v_cndmask_b32_e64 v52, v52, 0, vcc
	ds_write_b128 v60, v[42:45]
	ds_write_b128 v60, v[52:55] offset:16

; __device__ void conv_unit(LAS unsigned char* lds, const bf16_t* __restrict__ Z, bf16_t* __restrict__ MIX, int unit,
;                           const float* __restrict__ ccw, const float* __restrict__ ccb, const float* __restrict__ lng, const float* __restrict__ lnb, const float* __restrict__ scw) {
;     ...
;     __syncthreads();
;     { const int ch = tid & 255, half = tid >> 8; float acc[32]; const float bias = ccb[ch];
; #pragma unroll
;       for (int j = 0; j < 32; ++j) acc[j] = bias;
.LBB0_139:
	s_or_b64 exec, exec, s[10:11]
	v_lshlrev_b32_e32 v102, 2, v100
	s_waitcnt vmcnt(1)
	v_and_b32_e32 v2, 0x3fc, v102
	s_waitcnt lgkmcnt(0)
	s_barrier
	v_lshlrev_b32_e32 v4, 7, v100
	v_mov_b32_e32 v3, v1
	v_and_b32_e32 v4, 0xffff8000, v4
	s_mov_b32 s3, 0
	v_add3_u32 v103, 0, v4, v2
	v_add_u32_e32 v2, 0x18000, v2
	s_waitcnt vmcnt(0)
	v_mov_b32_e32 v4, v68
	v_mov_b32_e32 v5, v68
	v_mov_b32_e32 v6, v68
	v_mov_b32_e32 v7, v68
	v_mov_b32_e32 v8, v68
	v_mov_b32_e32 v9, v68
	v_mov_b32_e32 v10, v68
	v_mov_b32_e32 v11, v68
	v_mov_b32_e32 v12, v68
	v_mov_b32_e32 v13, v68
	v_mov_b32_e32 v14, v68
	v_mov_b32_e32 v15, v68
	v_mov_b32_e32 v16, v68
	v_mov_b32_e32 v17, v68
	v_mov_b32_e32 v18, v68
	v_mov_b32_e32 v19, v68
	v_mov_b32_e32 v20, v68
	v_mov_b32_e32 v21, v68
	v_mov_b32_e32 v22, v68
	v_mov_b32_e32 v23, v68
	v_mov_b32_e32 v24, v68
	v_mov_b32_e32 v25, v68
	v_mov_b32_e32 v26, v68
	v_mov_b32_e32 v27, v68
	v_mov_b32_e32 v28, v68
	v_mov_b32_e32 v29, v68
	v_mov_b32_e32 v30, v68
	v_mov_b32_e32 v31, v68
	v_mov_b32_e32 v32, v68
	v_mov_b32_e32 v33, v68
	v_mov_b32_e32 v34, v68
	v_mov_b32_e32 v35, v68
